# gdn producer loads only the needed 64-column half of the U tile; peeled last-chunk consumer copy removed
# speedup vs baseline: 1.0389x; 1.0015x over previous
; __device__ __forceinline__ float bf2f(bf16_t b) { return asf((unsigned)b << 16); }
; __device__ __forceinline__ int crow(int r, int hi) { return (r & 3) + 8 * (r >> 2) + 4 * hi; }
; __device__ __forceinline__ bf16x8 ldA_perm(const LAS bf16_t* p) { s16x4 a = *(const LAS s16x4*)p; s16x4 b = *(const LAS s16x4*)(p + 8); return (bf16x8){a[0], a[1], a[2], a[3], b[0], b[1], b[2], b[3]}; }
; #define LDS_BARRIER() do { asm volatile("s_waitcnt lgkmcnt(0)" ::: "memory"); __builtin_amdgcn_s_barrier(); asm volatile("" ::: "memory"); } while (0)
; #define GDN_LDF_WQ(F, td_) do { _Pragma("unroll") for (int tc = 0; tc < 2; ++tc) _Pragma("unroll") for (int s_ = 0; s_ < 2; ++s_) { const int ko_ = 32 * (td_) + 16 * s_ + 4 * hh; \
;                     F[tc * 2 + s_] = ldA_perm(WNs + (32 * tc + l31) * 136 + ko_); F[4 + tc * 2 + s_] = ldA_perm(QD + (32 * tc + l31) * 136 + ko_); } } while (0)
; __device__ __forceinline__ void gdn_scan(const Ctx& c, const Params& p, int e) {
;     ...
;             for (int n = 0; n < 128; ++n) {
;                 LDS_BARRIER();
;                 if (c.wave < 2) {
;                 const float gt = gtn; if (n + 1 < 128) gtn = GC[(size_t)bh * 128 + n + 1];
;                 f32x16 av[2];
; #pragma unroll
;                 for (int tc = 0; tc < 2; ++tc)
; #pragma unroll
;                     for (int r = 0; r < 16; ++r) av[tc][r] = bf2f(UT[(32 * tc + crow(r, hh)) * 136 + e0 + l31]);
;                 f32x16 ao[2] = {(f32x16){}, (f32x16){}};
;                 bf16x8 fa[8], fb[8];
;     ...
;                 GDN_LDF_WQ(fa, 0);
;                 GDN_LDF_WQ(fb, 1); GDN_MMA_WQ(fa, 0);
;                 GDN_LDF_WQ(fa, 2); GDN_MMA_WQ(fb, 1);
;                 GDN_LDF_WQ(fb, 3); GDN_MMA_WQ(fa, 2);
; #pragma unroll
;                 for (int tc = 0; tc < 2; ++tc)
; #pragma unroll
;                     for (int ts = 0; ts < 2; ++ts)
; #pragma unroll
;                         for (int s_ = 0; s_ < 2; ++s_) fa[tc * 4 + ts * 2 + s_] = ldA_perm(QK + (32 * tc + l31) * 72 + 32 * ts + 16 * s_ + 4 * hh);
;                 GDN_MMA_WQ(fb, 3);
.LBB0_524:
	s_add_i32 s21, s21, 1
	s_waitcnt lgkmcnt(0)
	s_barrier
	s_add_u32 s2, s2, 4
	s_addc_u32 s3, s3, 0
	s_cmpk_eq_i32 s21, 0x80
	s_cbranch_scc1 .Lgc_final
.LBB0_525:
	s_waitcnt lgkmcnt(0)
	s_barrier
	v_cndmask_b32_e64 v1, 0, 1, s[12:13]
	v_cmp_ne_u32_e64 s[4:5], 1, v1
	s_andn2_b64 vcc, exec, s[12:13]
	s_cbranch_vccnz .LBB0_524
	v_mov_b64_e32 v[252:253], s[2:3]
	v_add_u32_e32 v174, 0x4000, v186
	v_add_u32_e32 v175, 0x4000, v187
	global_load_dword v253, v[252:253], off
	v_add_u32_e32 v1, v168, v188
	ds_read2_b64 v[232:235], v14 offset0:0 offset1:2
	ds_read2_b64 v[236:239], v15 offset0:0 offset1:2
	ds_read2_b64 v[240:243], v14 offset0:4 offset1:6
	ds_read2_b64 v[244:247], v15 offset0:4 offset1:6
	ds_read2_b64 v[248:251], v174 offset0:128 offset1:130
	ds_read2_b64 v[2:5], v186 offset0:0 offset1:2
	v_add_u32_e32 v252, 0x1000, v1
	s_bitcmp1_b32 s21, 0
	s_cselect_b32 s35, 0x2400, 0
	v_cvt_pk_bf16_f32 v200, v64, v65
	v_cvt_pk_bf16_f32 v201, v66, v67
	v_cvt_pk_bf16_f32 v202, v68, v69
	v_cvt_pk_bf16_f32 v203, v70, v71
	v_cvt_pk_bf16_f32 v204, v72, v73
	v_cvt_pk_bf16_f32 v205, v74, v75
	v_cvt_pk_bf16_f32 v206, v76, v77
	v_cvt_pk_bf16_f32 v207, v78, v79
	s_waitcnt lgkmcnt(5)
	v_mfma_f32_32x32x16_bf16 v[80:95], v[232:235], v[6:9], 0
	ds_read2_b64 v[232:235], v175 offset0:128 offset1:130
	s_waitcnt lgkmcnt(5)
	v_mfma_f32_32x32x16_bf16 v[112:127], v[236:239], v[6:9], 0
	ds_read2_b64 v[236:239], v187 offset0:0 offset1:2
	s_waitcnt lgkmcnt(5)
	v_mfma_f32_32x32x16_bf16 v[80:95], v[240:243], v[10:13], v[80:95]
	ds_read2_b64 v[240:243], v174 offset0:132 offset1:134
	s_waitcnt lgkmcnt(5)
	v_mfma_f32_32x32x16_bf16 v[112:127], v[244:247], v[10:13], v[112:127]
	ds_read2_b64 v[244:247], v186 offset0:4 offset1:6
	s_waitcnt lgkmcnt(5)
	v_mfma_f32_32x32x16_bf16 v[80:95], v[248:251], v[200:203], v[80:95]
	ds_read2_b64 v[248:251], v175 offset0:132 offset1:134
	v_cvt_pk_bf16_f32 v208, v48, v49
	v_cvt_pk_bf16_f32 v209, v50, v51
	s_waitcnt lgkmcnt(5)
	v_mfma_f32_32x32x16_bf16 v[96:111], v[2:5], v[200:203], 0
	ds_read2_b64 v[2:5], v187 offset0:4 offset1:6
	v_cvt_pk_bf16_f32 v210, v52, v53
	v_cvt_pk_bf16_f32 v211, v54, v55
	s_waitcnt lgkmcnt(5)
	v_mfma_f32_32x32x16_bf16 v[112:127], v[232:235], v[200:203], v[112:127]
	ds_read2_b64 v[232:235], v174 offset0:136 offset1:138
	v_cvt_pk_bf16_f32 v212, v56, v57
	v_cvt_pk_bf16_f32 v213, v58, v59
	s_waitcnt lgkmcnt(5)
	v_mfma_f32_32x32x16_bf16 v[128:143], v[236:239], v[200:203], 0
	ds_read2_b64 v[236:239], v186 offset0:8 offset1:10
	v_cvt_pk_bf16_f32 v214, v60, v61
	v_cvt_pk_bf16_f32 v215, v62, v63
	s_waitcnt lgkmcnt(5)
	v_mfma_f32_32x32x16_bf16 v[80:95], v[240:243], v[204:207], v[80:95]
	ds_read2_b64 v[240:243], v175 offset0:136 offset1:138
	v_cvt_pk_bf16_f32 v216, v32, v33
	v_cvt_pk_bf16_f32 v217, v34, v35
	s_waitcnt lgkmcnt(5)
	v_mfma_f32_32x32x16_bf16 v[96:111], v[244:247], v[204:207], v[96:111]
	ds_read2_b64 v[244:247], v187 offset0:8 offset1:10
	v_cvt_pk_bf16_f32 v218, v36, v37
	v_cvt_pk_bf16_f32 v219, v38, v39
	s_waitcnt lgkmcnt(5)
	v_mfma_f32_32x32x16_bf16 v[112:127], v[248:251], v[204:207], v[112:127]
	ds_read2_b64 v[248:251], v174 offset0:140 offset1:142
	v_cvt_pk_bf16_f32 v220, v40, v41
	v_cvt_pk_bf16_f32 v221, v42, v43
	s_waitcnt lgkmcnt(5)
	v_mfma_f32_32x32x16_bf16 v[128:143], v[2:5], v[204:207], v[128:143]
	ds_read2_b64 v[2:5], v186 offset0:12 offset1:14
	v_cvt_pk_bf16_f32 v222, v44, v45
	v_cvt_pk_bf16_f32 v223, v46, v47
	s_waitcnt lgkmcnt(5)
	v_mfma_f32_32x32x16_bf16 v[80:95], v[232:235], v[208:211], v[80:95]
	ds_read2_b64 v[232:235], v175 offset0:140 offset1:142
	v_cvt_pk_bf16_f32 v224, v16, v17
	v_cvt_pk_bf16_f32 v225, v18, v19
	s_waitcnt lgkmcnt(5)
	v_mfma_f32_32x32x16_bf16 v[96:111], v[236:239], v[208:211], v[96:111]
	ds_read2_b64 v[236:239], v187 offset0:12 offset1:14
	v_cvt_pk_bf16_f32 v226, v20, v21
	v_cvt_pk_bf16_f32 v227, v22, v23
	s_waitcnt lgkmcnt(5)
	v_mfma_f32_32x32x16_bf16 v[112:127], v[240:243], v[208:211], v[112:127]
	ds_read2_b64 v[240:243], v174 offset0:144 offset1:146
	v_cvt_pk_bf16_f32 v228, v24, v25
	v_cvt_pk_bf16_f32 v229, v26, v27
	s_waitcnt lgkmcnt(5)
	v_mfma_f32_32x32x16_bf16 v[128:143], v[244:247], v[208:211], v[128:143]
	ds_read2_b64 v[244:247], v186 offset0:16 offset1:18
	v_cvt_pk_bf16_f32 v230, v28, v29
	v_cvt_pk_bf16_f32 v231, v30, v31
	s_waitcnt lgkmcnt(5)
	v_mfma_f32_32x32x16_bf16 v[80:95], v[248:251], v[212:215], v[80:95]
	ds_read2_b64 v[248:251], v175 offset0:144 offset1:146
	v_pk_mul_f32 v[64:65], v[64:65], v[150:151] op_sel_hi:[1,0]
	v_pk_mul_f32 v[66:67], v[66:67], v[150:151] op_sel_hi:[1,0]
	s_waitcnt lgkmcnt(5)
	v_mfma_f32_32x32x16_bf16 v[96:111], v[2:5], v[212:215], v[96:111]
	ds_read2_b64 v[2:5], v187 offset0:16 offset1:18
	v_pk_mul_f32 v[68:69], v[68:69], v[150:151] op_sel_hi:[1,0]
	v_pk_mul_f32 v[70:71], v[70:71], v[150:151] op_sel_hi:[1,0]
	s_waitcnt lgkmcnt(5)
	v_mfma_f32_32x32x16_bf16 v[112:127], v[232:235], v[212:215], v[112:127]
	ds_read2_b64 v[232:235], v174 offset0:148 offset1:150
	v_pk_mul_f32 v[72:73], v[72:73], v[150:151] op_sel_hi:[1,0]
	v_pk_mul_f32 v[74:75], v[74:75], v[150:151] op_sel_hi:[1,0]
	s_waitcnt lgkmcnt(5)
	v_mfma_f32_32x32x16_bf16 v[128:143], v[236:239], v[212:215], v[128:143]
	ds_read2_b64 v[236:239], v186 offset0:20 offset1:22
	v_pk_mul_f32 v[76:77], v[76:77], v[150:151] op_sel_hi:[1,0]
	v_pk_mul_f32 v[78:79], v[78:79], v[150:151] op_sel_hi:[1,0]
	s_waitcnt lgkmcnt(5)
	v_mfma_f32_32x32x16_bf16 v[80:95], v[240:243], v[216:219], v[80:95]
	ds_read2_b64 v[240:243], v175 offset0:148 offset1:150
	v_pk_mul_f32 v[48:49], v[48:49], v[150:151] op_sel_hi:[1,0]
	v_pk_mul_f32 v[50:51], v[50:51], v[150:151] op_sel_hi:[1,0]
	s_waitcnt lgkmcnt(5)
; #define GDN_LDF_K(F, tdp_) do { _Pragma("unroll") for (int t2_ = 0; t2_ < 2; ++t2_) _Pragma("unroll") for (int tc = 0; tc < 2; ++tc) _Pragma("unroll") for (int s_ = 0; s_ < 2; ++s_) \
;                     F[t2_ * 4 + tc * 2 + s_] = ldA_perm(KDT + (32 * (2 * (tdp_) + t2_) + l31) * 72 + 32 * tc + 16 * s_ + 4 * hh); } while (0)
; __device__ __forceinline__ void gdn_scan(const Ctx& c, const Params& p, int e) {
;     ...
;                 GDN_MMA_WQ(fb, 3);
;     ...
;                 bf16x8 Vb[2][2];
; #pragma unroll
;                 for (int tc = 0; tc < 2; ++tc) { Vb[tc][0] = pkfrag(av[tc], 0); Vb[tc][1] = pkfrag(av[tc], 1); }
;     ...
;                 GDN_LDF_K(fb, 0);
; #pragma unroll
;                 for (int ts = 0; ts < 2; ++ts)
; #pragma unroll
;                     for (int s_ = 0; s_ < 2; ++s_)
; #pragma unroll
;                         for (int tc = 0; tc < 2; ++tc) ao[tc] = __builtin_amdgcn_mfma_f32_32x32x16_bf16(fa[tc * 4 + ts * 2 + s_], Vb[ts][s_], ao[tc], 0, 0, 0);
;                 GDN_LDF_K(fa, 1); GDN_MMA_K(fb, 0);
;                 GDN_MMA_K(fa, 1);
	v_mfma_f32_32x32x16_bf16 v[96:111], v[244:247], v[216:219], v[96:111]
	ds_read2_b64 v[244:247], v187 offset0:20 offset1:22
	v_pk_mul_f32 v[52:53], v[52:53], v[150:151] op_sel_hi:[1,0]
	v_pk_mul_f32 v[54:55], v[54:55], v[150:151] op_sel_hi:[1,0]
	s_waitcnt lgkmcnt(5)
	v_mfma_f32_32x32x16_bf16 v[112:127], v[248:251], v[216:219], v[112:127]
	ds_read2_b64 v[248:251], v174 offset0:152 offset1:154
	v_pk_mul_f32 v[56:57], v[56:57], v[150:151] op_sel_hi:[1,0]
	v_pk_mul_f32 v[58:59], v[58:59], v[150:151] op_sel_hi:[1,0]
	s_waitcnt lgkmcnt(5)
	v_mfma_f32_32x32x16_bf16 v[128:143], v[2:5], v[216:219], v[128:143]
	ds_read2_b64 v[2:5], v175 offset0:152 offset1:154
	v_pk_mul_f32 v[60:61], v[60:61], v[150:151] op_sel_hi:[1,0]
	v_pk_mul_f32 v[62:63], v[62:63], v[150:151] op_sel_hi:[1,0]
	s_waitcnt lgkmcnt(5)
	v_mfma_f32_32x32x16_bf16 v[80:95], v[232:235], v[220:223], v[80:95]
	ds_read2_b64 v[232:235], v174 offset0:156 offset1:158
	v_pk_mul_f32 v[32:33], v[32:33], v[150:151] op_sel_hi:[1,0]
	v_pk_mul_f32 v[34:35], v[34:35], v[150:151] op_sel_hi:[1,0]
	s_waitcnt lgkmcnt(5)
	v_mfma_f32_32x32x16_bf16 v[96:111], v[236:239], v[220:223], v[96:111]
	ds_read2_b64 v[236:239], v175 offset0:156 offset1:158
	v_pk_mul_f32 v[36:37], v[36:37], v[150:151] op_sel_hi:[1,0]
	v_pk_mul_f32 v[38:39], v[38:39], v[150:151] op_sel_hi:[1,0]
	s_waitcnt lgkmcnt(5)
	v_mfma_f32_32x32x16_bf16 v[112:127], v[240:243], v[220:223], v[112:127]
	ds_read2_b64 v[240:243], v186 offset0:24 offset1:26
	v_pk_mul_f32 v[40:41], v[40:41], v[150:151] op_sel_hi:[1,0]
	v_pk_mul_f32 v[42:43], v[42:43], v[150:151] op_sel_hi:[1,0]
	s_waitcnt lgkmcnt(5)
	v_mfma_f32_32x32x16_bf16 v[128:143], v[244:247], v[220:223], v[128:143]
	ds_read2_b64 v[244:247], v187 offset0:24 offset1:26
	v_pk_mul_f32 v[44:45], v[44:45], v[150:151] op_sel_hi:[1,0]
	v_pk_mul_f32 v[46:47], v[46:47], v[150:151] op_sel_hi:[1,0]
	s_waitcnt lgkmcnt(5)
	v_mfma_f32_32x32x16_bf16 v[80:95], v[248:251], v[224:227], v[80:95]
	ds_read2_b64 v[248:251], v186 offset0:28 offset1:30
	v_pk_mul_f32 v[16:17], v[16:17], v[150:151] op_sel_hi:[1,0]
	v_pk_mul_f32 v[18:19], v[18:19], v[150:151] op_sel_hi:[1,0]
	s_waitcnt lgkmcnt(5)
	v_mfma_f32_32x32x16_bf16 v[112:127], v[2:5], v[224:227], v[112:127]
	ds_read2_b64 v[2:5], v187 offset0:28 offset1:30
	v_pk_mul_f32 v[20:21], v[20:21], v[150:151] op_sel_hi:[1,0]
	v_pk_mul_f32 v[22:23], v[22:23], v[150:151] op_sel_hi:[1,0]
	s_waitcnt lgkmcnt(5)
	v_mfma_f32_32x32x16_bf16 v[80:95], v[232:235], v[228:231], v[80:95]
	ds_read2_b64 v[232:235], v1 offset0:0 offset1:2
	v_pk_mul_f32 v[24:25], v[24:25], v[150:151] op_sel_hi:[1,0]
	v_pk_mul_f32 v[26:27], v[26:27], v[150:151] op_sel_hi:[1,0]
	s_waitcnt lgkmcnt(5)
	v_mfma_f32_32x32x16_bf16 v[112:127], v[236:239], v[228:231], v[112:127]
	ds_read2_b64 v[236:239], v252 offset0:64 offset1:66
	v_pk_mul_f32 v[28:29], v[28:29], v[150:151] op_sel_hi:[1,0]
	v_pk_mul_f32 v[30:31], v[30:31], v[150:151] op_sel_hi:[1,0]
	s_waitcnt lgkmcnt(5)
	v_mfma_f32_32x32x16_bf16 v[96:111], v[240:243], v[224:227], v[96:111]
	ds_read2_b64 v[240:243], v1 offset0:4 offset1:6
	s_waitcnt lgkmcnt(5)
	v_mfma_f32_32x32x16_bf16 v[128:143], v[244:247], v[224:227], v[128:143]
	ds_read2_b64 v[244:247], v252 offset0:68 offset1:70
	s_waitcnt lgkmcnt(5)
	v_mfma_f32_32x32x16_bf16 v[96:111], v[248:251], v[228:231], v[96:111]
	ds_read2_b64 v[248:251], v1 offset0:8 offset1:10
	s_waitcnt lgkmcnt(5)
	v_mfma_f32_32x32x16_bf16 v[128:143], v[2:5], v[228:231], v[128:143]
	ds_read2_b64 v[2:5], v252 offset0:72 offset1:74
	s_waitcnt vmcnt(0)
	v_mov_b32_e32 v150, v253
	s_nop 3
	v_cvt_pk_bf16_f32 v80, v80, v81
	v_cvt_pk_bf16_f32 v81, v82, v83
	v_cvt_pk_bf16_f32 v82, v84, v85
	v_cvt_pk_bf16_f32 v83, v86, v87
	v_cvt_pk_bf16_f32 v84, v88, v89
	v_cvt_pk_bf16_f32 v85, v90, v91
	v_cvt_pk_bf16_f32 v86, v92, v93
	v_cvt_pk_bf16_f32 v87, v94, v95
	v_cvt_pk_bf16_f32 v112, v112, v113
	v_cvt_pk_bf16_f32 v113, v114, v115
	v_cvt_pk_bf16_f32 v114, v116, v117
	v_cvt_pk_bf16_f32 v115, v118, v119
	v_cvt_pk_bf16_f32 v116, v120, v121
	v_cvt_pk_bf16_f32 v117, v122, v123
	v_cvt_pk_bf16_f32 v118, v124, v125
	v_cvt_pk_bf16_f32 v119, v126, v127
	v_add_u32_e32 v174, v169, v188
	v_add_u32_e32 v174, 0xcc00, v174
	v_add_u32_e32 v175, 0x1200, v174
	v_add_u32_e32 v253, 0x1200, v175
	s_waitcnt lgkmcnt(5)
	v_mfma_f32_32x32x16_bf16 v[96:111], v[232:235], v[80:83], v[96:111]
	ds_read2_b64 v[232:235], v1 offset0:12 offset1:14
	s_waitcnt lgkmcnt(5)
	v_mfma_f32_32x32x16_bf16 v[128:143], v[236:239], v[80:83], v[128:143]
	ds_read2_b64 v[236:239], v252 offset0:76 offset1:78
	v_add_u32_e32 v252, 0x1200, v253
	s_waitcnt lgkmcnt(5)
	v_mfma_f32_32x32x16_bf16 v[96:111], v[240:243], v[84:87], v[96:111]
	ds_read2_b64 v[240:243], v174 offset0:0 offset1:2
	s_waitcnt lgkmcnt(5)
	v_mfma_f32_32x32x16_bf16 v[128:143], v[244:247], v[84:87], v[128:143]
	ds_read2_b64 v[244:247], v175 offset0:0 offset1:2
	s_waitcnt lgkmcnt(5)
	v_mfma_f32_32x32x16_bf16 v[96:111], v[248:251], v[112:115], v[96:111]
	ds_read2_b64 v[248:251], v253 offset0:0 offset1:2
	s_waitcnt lgkmcnt(5)
	v_mfma_f32_32x32x16_bf16 v[128:143], v[2:5], v[112:115], v[128:143]
	ds_read2_b64 v[2:5], v252 offset0:0 offset1:2
	s_waitcnt lgkmcnt(5)
	v_mfma_f32_32x32x16_bf16 v[96:111], v[232:235], v[116:119], v[96:111]
	ds_read2_b64 v[232:235], v174 offset0:4 offset1:6
	s_waitcnt lgkmcnt(5)
	v_mfma_f32_32x32x16_bf16 v[128:143], v[236:239], v[116:119], v[128:143]
	ds_read2_b64 v[236:239], v175 offset0:4 offset1:6
	v_add_u32_e32 v1, s35, v195
	v_add_u32_e32 v1, v1, v190
	s_waitcnt lgkmcnt(5)
	v_mfma_f32_32x32x16_bf16 v[64:79], v[240:243], v[80:83], v[64:79]
	ds_read2_b64 v[240:243], v253 offset0:4 offset1:6
	s_waitcnt lgkmcnt(5)
; #define LAS __attribute__((address_space(3)))
; __device__ __forceinline__ bf16_t f2bf(float f) { return (bf16_t)(pk2(f, 0.f) & 0xffffu); }
; __device__ __forceinline__ int crow(int r, int hi) { return (r & 3) + 8 * (r >> 2) + 4 * hi; }
; #define GDN_LDF_K(F, tdp_) do { _Pragma("unroll") for (int t2_ = 0; t2_ < 2; ++t2_) _Pragma("unroll") for (int tc = 0; tc < 2; ++tc) _Pragma("unroll") for (int s_ = 0; s_ < 2; ++s_) \
;                     F[t2_ * 4 + tc * 2 + s_] = ldA_perm(KDT + (32 * (2 * (tdp_) + t2_) + l31) * 72 + 32 * tc + 16 * s_ + 4 * hh); } while (0)
; __device__ __forceinline__ void gdn_scan(const Ctx& c, const Params& p, int e) {
;     ...
;         const int bh = item >> 1, dvh = item & 1, h = bh % 6, b = bh / 6;
;         const int e0 = 64 * dvh + 32 * (c.wave & 1);
;     ...
;                         for (int tc = 0; tc < 2; ++tc) ao[tc] = __builtin_amdgcn_mfma_f32_32x32x16_bf16(fa[tc * 4 + ts * 2 + s_], Vb[ts][s_], ao[tc], 0, 0, 0);
;                 GDN_LDF_K(fa, 1); GDN_MMA_K(fb, 0);
;                 GDN_MMA_K(fa, 1);
;     ...
;                 LAS bf16_t* ob = OTb + (n & 1) * 4608;
; #pragma unroll
;                 for (int tc = 0; tc < 2; ++tc)
; #pragma unroll
;                     for (int r = 0; r < 16; ++r) ob[(32 * tc + crow(r, hh)) * 72 + 32 * (c.wave & 1) + l31] = f2bf(ao[tc][r]);
	v_mfma_f32_32x32x16_bf16 v[48:63], v[244:247], v[80:83], v[48:63]
	ds_read2_b64 v[244:247], v252 offset0:4 offset1:6
	s_waitcnt lgkmcnt(5)
	v_mfma_f32_32x32x16_bf16 v[32:47], v[248:251], v[80:83], v[32:47]
	ds_read2_b64 v[248:251], v174 offset0:8 offset1:10
	s_waitcnt lgkmcnt(5)
	v_mfma_f32_32x32x16_bf16 v[16:31], v[2:5], v[80:83], v[16:31]
	ds_read2_b64 v[2:5], v175 offset0:8 offset1:10
	v_cvt_pk_bf16_f32 v88, v96, v97
	ds_write_b16 v1, v88 offset:0
	ds_write_b16_d16_hi v1, v88 offset:144
	s_waitcnt lgkmcnt(7)
	v_mfma_f32_32x32x16_bf16 v[64:79], v[232:235], v[84:87], v[64:79]
	ds_read2_b64 v[232:235], v253 offset0:8 offset1:10
	v_cvt_pk_bf16_f32 v89, v98, v99
	ds_write_b16 v1, v89 offset:288
	ds_write_b16_d16_hi v1, v89 offset:432
	s_waitcnt lgkmcnt(9)
	v_mfma_f32_32x32x16_bf16 v[48:63], v[236:239], v[84:87], v[48:63]
	ds_read2_b64 v[236:239], v252 offset0:8 offset1:10
	v_cvt_pk_bf16_f32 v90, v100, v101
	ds_write_b16 v1, v90 offset:1152
	ds_write_b16_d16_hi v1, v90 offset:1296
	s_waitcnt lgkmcnt(11)
	v_mfma_f32_32x32x16_bf16 v[32:47], v[240:243], v[84:87], v[32:47]
	ds_read2_b64 v[240:243], v174 offset0:12 offset1:14
	v_cvt_pk_bf16_f32 v91, v102, v103
	ds_write_b16 v1, v91 offset:1440
	ds_write_b16_d16_hi v1, v91 offset:1584
	s_waitcnt lgkmcnt(13)
	v_mfma_f32_32x32x16_bf16 v[16:31], v[244:247], v[84:87], v[16:31]
	ds_read2_b64 v[244:247], v175 offset0:12 offset1:14
	v_cvt_pk_bf16_f32 v88, v104, v105
	ds_write_b16 v1, v88 offset:2304
	s_waitcnt lgkmcnt(7)
	ds_write_b16_d16_hi v1, v88 offset:2448
	v_mfma_f32_32x32x16_bf16 v[64:79], v[248:251], v[112:115], v[64:79]
	ds_read2_b64 v[248:251], v253 offset0:12 offset1:14
	v_cvt_pk_bf16_f32 v89, v106, v107
	ds_write_b16 v1, v89 offset:2592
	ds_write_b16_d16_hi v1, v89 offset:2736
	v_mfma_f32_32x32x16_bf16 v[48:63], v[2:5], v[112:115], v[48:63]
	ds_read2_b64 v[2:5], v252 offset0:12 offset1:14
	v_cvt_pk_bf16_f32 v90, v108, v109
	ds_write_b16 v1, v90 offset:3456
	ds_write_b16_d16_hi v1, v90 offset:3600
	v_mfma_f32_32x32x16_bf16 v[32:47], v[232:235], v[112:115], v[32:47]
	v_cvt_pk_bf16_f32 v91, v110, v111
	ds_write_b16 v1, v91 offset:3744
	s_waitcnt lgkmcnt(7)
	ds_write_b16_d16_hi v1, v91 offset:3888
	v_cvt_pk_bf16_f32 v88, v128, v129
	ds_write_b16 v1, v88 offset:4608
	ds_write_b16_d16_hi v1, v88 offset:4752
	v_mfma_f32_32x32x16_bf16 v[16:31], v[236:239], v[112:115], v[16:31]
	v_cvt_pk_bf16_f32 v89, v130, v131
	ds_write_b16 v1, v89 offset:4896
	ds_write_b16_d16_hi v1, v89 offset:5040
	v_cvt_pk_bf16_f32 v90, v132, v133
	ds_write_b16 v1, v90 offset:5760
	ds_write_b16_d16_hi v1, v90 offset:5904
	v_mfma_f32_32x32x16_bf16 v[64:79], v[240:243], v[116:119], v[64:79]
	v_cvt_pk_bf16_f32 v91, v134, v135
	ds_write_b16 v1, v91 offset:6048
	s_waitcnt lgkmcnt(7)
	ds_write_b16_d16_hi v1, v91 offset:6192
	v_cvt_pk_bf16_f32 v88, v136, v137
	ds_write_b16 v1, v88 offset:6912
	ds_write_b16_d16_hi v1, v88 offset:7056
	v_mfma_f32_32x32x16_bf16 v[48:63], v[244:247], v[116:119], v[48:63]
	v_cvt_pk_bf16_f32 v89, v138, v139
	ds_write_b16 v1, v89 offset:7200
	ds_write_b16_d16_hi v1, v89 offset:7344
	v_cvt_pk_bf16_f32 v90, v140, v141
	ds_write_b16 v1, v90 offset:8064
	ds_write_b16_d16_hi v1, v90 offset:8208
	v_mfma_f32_32x32x16_bf16 v[32:47], v[248:251], v[116:119], v[32:47]
	v_cvt_pk_bf16_f32 v91, v142, v143
	ds_write_b16 v1, v91 offset:8352
	s_waitcnt lgkmcnt(7)
	ds_write_b16_d16_hi v1, v91 offset:8496
	v_mfma_f32_32x32x16_bf16 v[16:31], v[2:5], v[116:119], v[16:31]
	s_branch .LBB0_524
.Lgc_final:
	s_waitcnt lgkmcnt(0)
	s_barrier
	s_mov_b64 s[2:3], 0
.LBB0_530:
	s_and_b64 vcc, exec, s[2:3]
	s_cbranch_vccz .LBB0_521
	s_mul_hi_i32 s2, s20, 0x2aaaaaab
	s_lshr_b32 s3, s2, 31
	s_add_i32 s2, s2, s3
	s_mul_i32 s3, s2, 6
	s_sub_i32 s3, s20, s3
	s_waitcnt vmcnt(0)
	v_mov_b32_e32 v97, v165
	s_lshl_b32 s4, s2, 13
	v_ashrrev_i32_e32 v64, 4, v97
	v_lshlrev_b32_e32 v1, 3, v97
	s_lshl_b32 s2, s3, 7
	s_waitcnt lgkmcnt(0)
	v_and_b32_e32 v12, 0x78, v1
	s_ashr_i32 s5, s4, 31
	v_ashrrev_i32_e32 v65, 31, v64
	s_ashr_i32 s3, s2, 31
	v_lshl_add_u64 v[2:3], v[64:65], 0, s[4:5]
	v_or_b32_e32 v102, s2, v12
	v_mov_b32_e32 v103, s3
	s_movk_i32 s35, 0x300
	v_and_b32_e32 v66, 56, v1
	v_mad_u64_u32 v[6:7], s[20:21], v2, s35, v[102:103]
	v_add_u32_e32 v1, 0x100, v97
	v_mad_i32_i24 v7, v3, s35, v7
	v_mov_b64_e32 v[10:11], s[16:17]
	v_ashrrev_i32_e32 v106, 4, v1
	v_mad_u64_u32 v[4:5], s[20:21], v2, s69, v[10:11]
	v_lshlrev_b64 v[6:7], 1, v[6:7]
	v_ashrrev_i32_e32 v107, 31, v106
	v_mad_i32_i24 v5, v3, s69, v5
	s_lshl_b64 s[20:21], s[2:3], 1
	v_lshlrev_b32_e32 v114, 4, v97
	v_lshl_add_u64 v[68:69], s[8:9], 0, v[6:7]
	v_lshl_add_u64 v[78:79], s[6:7], 0, v[6:7]
	v_lshl_add_u64 v[6:7], v[106:107], 0, s[4:5]
	v_lshl_add_u64 v[8:9], v[4:5], 0, s[20:21]
	v_lshlrev_b32_e32 v104, 1, v12
	v_mov_b32_e32 v105, v0
	v_and_b32_e32 v4, 0x80, v114
	v_mov_b32_e32 v5, v0
	v_mad_u64_u32 v[32:33], s[2:3], v6, s69, v[10:11]
	v_lshl_add_u64 v[14:15], v[8:9], 0, v[104:105]
	v_lshl_add_u64 v[12:13], v[8:9], 0, v[4:5]
	v_lshlrev_b32_e32 v8, 1, v66
	v_mov_b32_e32 v9, v0
	v_mad_i32_i24 v33, v7, s69, v33
	v_lshl_add_u64 v[12:13], v[12:13], 0, v[8:9]
	v_lshl_add_u64 v[32:33], v[32:33], 0, s[20:21]
	global_load_dwordx4 v[16:19], v[14:15], off offset:1536
	global_load_dwordx4 v[20:23], v[12:13], off offset:3072
	v_add_co_u32_e32 v12, vcc, s47, v14
	v_lshl_add_u64 v[32:33], v[32:33], 0, v[4:5]
	s_nop 0
	v_addc_co_u32_e32 v13, vcc, 0, v15, vcc
	v_lshl_add_u64 v[36:37], v[32:33], 0, v[8:9]
	s_movk_i32 s0, 0x6000
	global_load_dwordx4 v[24:27], v[68:69], off
	global_load_dwordx4 v[28:31], v[78:79], off
	global_load_dwordx4 v[32:35], v[12:13], off offset:2048
	s_nop 0
	global_load_dwordx4 v[36:39], v[36:37], off offset:3072
	v_add_co_u32_e32 v12, vcc, s0, v68
	s_mov_b32 s39, 0x3c000
	s_nop 0
	v_addc_co_u32_e32 v13, vcc, 0, v69, vcc
	v_add_co_u32_e32 v44, vcc, s0, v78
	v_add_u32_e32 v94, 0x200, v97
	s_nop 0
	v_addc_co_u32_e32 v45, vcc, 0, v79, vcc
	v_add_co_u32_e32 v48, vcc, s39, v14
	v_add_u32_e32 v95, 0x300, v97
	s_nop 0
	v_addc_co_u32_e32 v49, vcc, 0, v15, vcc
	v_add_co_u32_e32 v56, vcc, s62, v68
	v_ashrrev_i32_e32 v108, 4, v94
	s_nop 0
	v_addc_co_u32_e32 v57, vcc, 0, v69, vcc
	v_add_co_u32_e32 v60, vcc, s62, v78
	s_mov_b32 s42, 0x5a000
	s_nop 0
	v_addc_co_u32_e32 v61, vcc, 0, v79, vcc
	v_ashrrev_i32_e32 v110, 4, v95
	v_ashrrev_i32_e32 v109, 31, v108
	v_add_co_u32_e32 v70, vcc, s42, v14
	v_ashrrev_i32_e32 v111, 31, v110
	global_load_dwordx4 v[40:43], v[12:13], off
	s_nop 0
	global_load_dwordx4 v[44:47], v[44:45], off
	v_lshl_add_u64 v[12:13], v[108:109], 0, s[4:5]
	v_addc_co_u32_e32 v71, vcc, 0, v15, vcc
	v_lshl_add_u64 v[14:15], v[110:111], 0, s[4:5]
	v_mad_u64_u32 v[50:51], s[2:3], v12, s69, v[10:11]
	v_mad_u64_u32 v[72:73], s[2:3], v14, s69, v[10:11]
	v_mad_i32_i24 v51, v13, s69, v51
	v_mad_i32_i24 v73, v15, s69, v73
	v_add_co_u32_e32 v68, vcc, s63, v68
	v_lshl_add_u64 v[50:51], v[50:51], 0, s[20:21]
	v_lshl_add_u64 v[72:73], v[72:73], 0, s[20:21]
	v_addc_co_u32_e32 v69, vcc, 0, v69, vcc
	v_lshl_add_u64 v[50:51], v[50:51], 0, v[4:5]
	v_lshl_add_u64 v[72:73], v[72:73], 0, v[4:5]
	v_add_co_u32_e32 v82, vcc, s63, v78
	v_lshl_add_u64 v[52:53], v[50:51], 0, v[8:9]
	v_lshl_add_u64 v[74:75], v[72:73], 0, v[8:9]
	v_addc_co_u32_e32 v83, vcc, 0, v79, vcc
	global_load_dwordx4 v[48:51], v[48:49], off offset:2560
	s_nop 0
	global_load_dwordx4 v[52:55], v[52:53], off offset:3072
	s_nop 0
	global_load_dwordx4 v[56:59], v[56:57], off
	s_nop 0
	global_load_dwordx4 v[60:63], v[60:61], off
	s_nop 0
	global_load_dwordx4 v[70:73], v[70:71], off offset:3072
	s_nop 0
	global_load_dwordx4 v[74:77], v[74:75], off offset:3072
	s_nop 0
	global_load_dwordx4 v[78:81], v[68:69], off
	s_nop 0
	global_load_dwordx4 v[82:85], v[82:83], off
	v_ashrrev_i32_e32 v68, 3, v97
	v_ashrrev_i32_e32 v69, 31, v68
	v_lshl_add_u64 v[112:113], v[68:69], 0, s[4:5]
	v_mad_u64_u32 v[86:87], s[2:3], v112, s69, v[10:11]
	v_mad_i32_i24 v87, v113, s69, v87
	v_lshl_add_u64 v[86:87], v[86:87], 0, s[20:21]
	v_lshl_add_u64 v[86:87], v[86:87], 0, v[8:9]
	s_movk_i32 s5, 0x1000
	v_add_co_u32_e32 v88, vcc, s5, v86
	s_mov_b32 s44, 0x3d000
	s_nop 0
	v_addc_co_u32_e32 v89, vcc, 0, v87, vcc
	v_add_co_u32_e32 v90, vcc, s44, v86
	v_mul_lo_u32 v67, v64, s36
	s_nop 0
	v_addc_co_u32_e32 v91, vcc, 0, v87, vcc
	global_load_dwordx4 v[86:89], v[88:89], off offset:512
	s_nop 0
	global_load_dwordx4 v[98:101], v[90:91], off offset:1536
	v_add3_u32 v91, s80, v104, v67
	s_waitcnt vmcnt(0) lgkmcnt(0)
; #define LDS_BARRIER() do { asm volatile("s_waitcnt lgkmcnt(0)" ::: "memory"); __builtin_amdgcn_s_barrier(); asm volatile("" ::: "memory"); } while (0)
; __device__ __forceinline__ void gdn_scan(const Ctx& c, const Params& p, int e) {
;     ...
;         if (producer) {
;             int pt_ = ptid; asm volatile("" : "+v"(pt_));
;             u32x4 tq[4], tk[4], tw[4], tu[4], tqk[2];
;             const int prow = pt_ >> 4, pc8 = (pt_ & 15) * 8;
;             const int qrow = pt_ >> 3, qc8 = (pt_ & 7) * 8;
;             GDN_LOAD_TILES(0); GDN_STORE_TILES();
;             for (int n = 0; n < 128; ++n) {
;                 LDS_BARRIER();
;                 if (n + 1 < 128) GDN_LOAD_TILES(n + 1);
	ds_write_b128 v91, v[16:19]
	ds_write_b128 v91, v[24:27] offset:17408
	ds_write_b128 v91, v[28:31] offset:34816
	s_movk_i32 s2, 0x90
	v_lshrrev_b32_e32 v116, 3, v94
	v_add_u32_e32 v96, s80, v8
	v_mul_lo_u32 v116, v116, s2
	v_ashrrev_i32_e32 v1, 3, v1
	v_add_u32_e32 v94, v96, v116
	v_lshrrev_b32_e32 v116, 3, v95
	v_mul_lo_u32 v90, v68, s2
	v_mul_lo_u32 v67, v1, s2
	v_mul_lo_u32 v116, v116, s2
	s_or_b32 s2, s4, 64
	v_add_u32_e32 v95, v96, v116
	v_add_u32_e32 v116, s24, v8
	s_ashr_i32 s3, s2, 31
	v_add_u32_e32 v92, v96, v90
	v_add_u32_e32 v93, v96, v67
	v_add_u32_e32 v96, v116, v90
	v_lshl_add_u64 v[116:117], v[64:65], 0, s[2:3]
	v_mad_u64_u32 v[118:119], s[40:41], v116, s69, v[10:11]
	v_mad_u64_u32 v[120:121], s[40:41], v116, s35, v[102:103]
	v_mad_i32_i24 v119, v117, s69, v119
	v_mad_i32_i24 v121, v117, s35, v121
	v_lshl_add_u64 v[116:117], v[118:119], 0, s[20:21]
	v_lshl_add_u64 v[64:65], v[116:117], 0, v[104:105]
	ds_write_b128 v92, v[20:23] offset:52224
	ds_write_b128 v91, v[32:35] offset:4352
	ds_write_b128 v91, v[40:43] offset:21760
	ds_write_b128 v91, v[44:47] offset:39168
	v_lshlrev_b64 v[120:121], 1, v[120:121]
	v_add_co_u32_e32 v132, vcc, s47, v64
	ds_write_b128 v93, v[36:39] offset:52224
	ds_write_b128 v91, v[48:51] offset:8704
	ds_write_b128 v91, v[56:59] offset:26112
	ds_write_b128 v91, v[60:63] offset:43520
	ds_write_b128 v94, v[52:55] offset:52224
	ds_write_b128 v91, v[70:73] offset:13056
	ds_write_b128 v91, v[78:81] offset:30464
	ds_write_b128 v91, v[82:85] offset:47872
	v_lshl_add_u64 v[224:225], s[8:9], 0, v[120:121]
	v_addc_co_u32_e32 v133, vcc, 0, v65, vcc
	v_add_co_u32_e32 v136, vcc, s0, v224
	v_lshl_add_u64 v[226:227], s[6:7], 0, v[120:121]
	s_nop 0
	v_addc_co_u32_e32 v137, vcc, 0, v225, vcc
	v_add_co_u32_e32 v140, vcc, s0, v226
	v_lshl_add_u64 v[134:135], v[106:107], 0, s[2:3]
	s_nop 0
	v_addc_co_u32_e32 v141, vcc, 0, v227, vcc
	v_add_co_u32_e32 v204, vcc, s39, v64
	v_lshl_add_u64 v[206:207], v[108:109], 0, s[2:3]
	s_nop 0
	v_addc_co_u32_e32 v205, vcc, 0, v65, vcc
	v_add_co_u32_e32 v208, vcc, s62, v224
	v_lshl_add_u64 v[220:221], v[110:111], 0, s[2:3]
	v_mad_u64_u32 v[200:201], s[40:41], v134, s69, v[10:11]
	v_mad_u64_u32 v[216:217], s[40:41], v206, s69, v[10:11]
	v_addc_co_u32_e32 v209, vcc, 0, v225, vcc
	v_mad_u64_u32 v[222:223], s[40:41], v220, s69, v[10:11]
	ds_write_b128 v95, v[74:77] offset:52224
	ds_write_b128 v96, v[86:89]
	ds_write_b128 v96, v[98:101] offset:4608
	v_lshl_add_u64 v[116:117], v[116:117], 0, v[4:5]
	v_mad_i32_i24 v201, v135, s69, v201
	v_mad_i32_i24 v217, v207, s69, v217
	v_add_co_u32_e32 v212, vcc, s62, v226
	v_mad_i32_i24 v223, v221, s69, v223
	v_lshl_add_u64 v[128:129], v[116:117], 0, v[8:9]
	v_lshl_add_u64 v[134:135], v[200:201], 0, s[20:21]
	v_lshl_add_u64 v[206:207], v[216:217], 0, s[20:21]
	v_addc_co_u32_e32 v213, vcc, 0, v227, vcc
	v_lshl_add_u64 v[220:221], v[222:223], 0, s[20:21]
	global_load_dwordx4 v[116:119], v[64:65], off offset:1536
	s_nop 0
	global_load_dwordx4 v[128:131], v[128:129], off offset:3072
	v_lshl_add_u64 v[134:135], v[134:135], 0, v[4:5]
	v_lshl_add_u64 v[206:207], v[206:207], 0, v[4:5]
	v_add_co_u32_e32 v64, vcc, s42, v64
	v_lshl_add_u64 v[220:221], v[220:221], 0, v[4:5]
	v_lshl_add_u64 v[200:201], v[134:135], 0, v[8:9]
	v_lshl_add_u64 v[216:217], v[206:207], 0, v[8:9]
	v_addc_co_u32_e32 v65, vcc, 0, v65, vcc
	v_lshl_add_u64 v[232:233], v[220:221], 0, v[8:9]
	global_load_dwordx4 v[120:123], v[224:225], off
	global_load_dwordx4 v[124:127], v[226:227], off
	s_nop 0
	global_load_dwordx4 v[132:135], v[132:133], off offset:2048
	s_nop 0
	global_load_dwordx4 v[200:203], v[200:201], off offset:3072
	s_nop 0
	global_load_dwordx4 v[136:139], v[136:137], off
	s_nop 0
	global_load_dwordx4 v[140:143], v[140:141], off
	s_nop 0
	global_load_dwordx4 v[204:207], v[204:205], off offset:2560
	s_nop 0
	global_load_dwordx4 v[216:219], v[216:217], off offset:3072
	s_nop 0
	global_load_dwordx4 v[208:211], v[208:209], off
	s_nop 0
	global_load_dwordx4 v[212:215], v[212:213], off
	s_nop 0
	global_load_dwordx4 v[220:223], v[64:65], off offset:3072
	s_nop 0
	global_load_dwordx4 v[232:235], v[232:233], off offset:3072
	v_add_co_u32_e32 v64, vcc, s63, v224
	s_nop 1
	v_addc_co_u32_e32 v65, vcc, 0, v225, vcc
	v_add_co_u32_e32 v228, vcc, s63, v226
	s_nop 1
	v_addc_co_u32_e32 v229, vcc, 0, v227, vcc
	global_load_dwordx4 v[224:227], v[64:65], off
	s_nop 0
	global_load_dwordx4 v[228:231], v[228:229], off
	v_lshl_add_u64 v[64:65], v[68:69], 0, s[2:3]
	v_mad_u64_u32 v[10:11], s[2:3], v64, s69, v[10:11]
	v_mad_i32_i24 v11, v65, s69, v11
	v_lshl_add_u64 v[10:11], v[10:11], 0, s[20:21]
	v_lshl_add_u64 v[10:11], v[10:11], 0, v[8:9]
	v_add_co_u32_e32 v64, vcc, s5, v10
	s_add_u32 s3, s74, s20
	s_nop 0
	v_addc_co_u32_e32 v65, vcc, 0, v11, vcc
	v_add_co_u32_e32 v10, vcc, s44, v10
	s_addc_u32 s5, s75, s21
	s_nop 0
	v_addc_co_u32_e32 v11, vcc, 0, v11, vcc
	global_load_dwordx4 v[236:239], v[64:65], off offset:512
	global_load_dwordx4 v[240:243], v[10:11], off offset:1536
	s_lshl_b32 s35, s34, 1
	s_add_u32 s40, s3, s35
	s_addc_u32 s41, s5, 0
	v_add_u32_e32 v69, s25, v8
	v_lshl_add_u64 v[70:71], s[40:41], 0, v[8:9]
	v_and_b32_e32 v8, 7, v97
	v_lshlrev_b32_e32 v8, 4, v8
	v_mad_u64_u32 v[10:11], s[40:41], v112, s69, v[8:9]
	v_mad_i32_i24 v11, v113, s69, v11
	v_lshl_add_u64 v[76:77], s[22:23], 0, v[10:11]
	v_mad_u64_u32 v[10:11], s[40:41], v14, s69, v[4:5]
	v_mad_i32_i24 v11, v15, s69, v11
	v_lshl_add_u64 v[10:11], v[10:11], 0, v[8:9]
	v_lshl_add_u64 v[78:79], s[18:19], 0, v[10:11]
	v_mad_u64_u32 v[10:11], s[40:41], v12, s69, v[4:5]
	v_mad_i32_i24 v11, v13, s69, v11
	v_lshl_add_u64 v[10:11], v[10:11], 0, v[8:9]
	v_lshl_add_u64 v[80:81], s[18:19], 0, v[10:11]
	v_mad_u64_u32 v[10:11], s[40:41], v6, s69, v[4:5]
	v_mad_i32_i24 v11, v7, s69, v11
	v_mad_u64_u32 v[4:5], s[40:41], v2, s69, v[4:5]
	v_lshl_add_u64 v[6:7], v[10:11], 0, v[8:9]
	v_mad_i32_i24 v5, v3, s69, v5
	v_lshl_add_u64 v[82:83], s[18:19], 0, v[6:7]
	v_and_b32_e32 v6, 0xf0, v114
	v_mov_b32_e32 v7, v0
	v_lshl_add_u64 v[4:5], v[4:5], 0, v[8:9]
	v_mad_u64_u32 v[10:11], s[40:41], v2, s69, v[6:7]
	v_lshl_add_u64 v[86:87], s[18:19], 0, v[4:5]
	v_mad_u64_u32 v[4:5], s[40:41], v2, s50, 0
	v_mad_i32_i24 v11, v3, s69, v11
	v_mad_i32_i24 v3, v3, s50, v5
	v_or_b32_e32 v2, v4, v6
	s_mov_b32 s2, 0
	v_add_u32_e32 v72, s4, v1
	v_add_u32_e32 v74, s4, v68
	v_lshl_add_u64 v[84:85], s[22:23], 0, v[10:11]
	v_lshl_add_u64 v[88:89], s[22:23], 0, v[2:3]
	s_mov_b32 s2, -1
	v_subrev_u32_e32 v72, 64, v72
	v_subrev_u32_e32 v74, 64, v74
	s_mov_b32 s98, 0xff00ff
	s_mov_b32 s99, 0xff00ff00
	s_cmp_eq_u32 s34, 0
	s_cselect_b32 s98, s98, s99
	s_mov_b32 s99, s98

.Lgp_e_nost:
	s_cmpk_eq_i32 s2, 0x7d
	s_cbranch_scc1 .Lgp_e_nold
	v_lshl_add_u64 v[50:51], v[84:85], 0, s[20:21]
	v_add_co_u32_e32 v2, vcc, 0x81f1000, v50
	v_lshl_add_u64 v[62:63], v[88:89], 0, s[20:21]
	s_nop 0
	v_addc_co_u32_e32 v3, vcc, 0, v51, vcc
	v_add_co_u32_e32 v10, vcc, 0x1a230000, v62
	s_nop 0
	v_addc_co_u32_e32 v11, vcc, 0, v63, vcc
	v_add_co_u32_e32 v14, vcc, 0x17230000, v62
	global_load_dwordx4 v[2:5], v[2:3], off offset:1536
	s_nop 0
	v_addc_co_u32_e32 v15, vcc, 0, v63, vcc
	v_add_co_u32_e32 v18, vcc, 0x820f000, v50
	global_load_dwordx4 v[10:13], v[10:11], off
	s_nop 0
	v_addc_co_u32_e32 v19, vcc, 0, v51, vcc
	v_add_co_u32_e32 v26, vcc, 0x1a236000, v62
	v_lshl_add_u64 v[6:7], v[86:87], 0, s[20:21]
	s_nop 0
	v_addc_co_u32_e32 v27, vcc, 0, v63, vcc
	v_add_co_u32_e32 v30, vcc, 0x17236000, v62
	s_mov_b64 exec, s[98:99]
	global_load_dwordx4 v[14:17], v[14:15], off
	s_mov_b64 exec, -1
	s_nop 0
	v_addc_co_u32_e32 v31, vcc, 0, v63, vcc
	v_add_co_u32_e32 v34, vcc, 0x822d000, v50
	global_load_dwordx4 v[6:9], v[6:7], off
	s_nop 0
	v_addc_co_u32_e32 v35, vcc, 0, v51, vcc
	v_add_co_u32_e32 v42, vcc, 0x1a23c000, v62
	global_load_dwordx4 v[18:21], v[18:19], off offset:2048
	s_nop 0
	v_addc_co_u32_e32 v43, vcc, 0, v63, vcc
	global_load_dwordx4 v[26:29], v[26:27], off
	v_add_co_u32_e32 v46, vcc, 0x1723c000, v62
	v_lshl_add_u64 v[22:23], v[82:83], 0, s[20:21]
	s_mov_b64 exec, s[98:99]
	global_load_dwordx4 v[30:33], v[30:31], off
	s_mov_b64 exec, -1
	v_addc_co_u32_e32 v47, vcc, 0, v63, vcc
	global_load_dwordx4 v[22:25], v[22:23], off
	v_add_co_u32_e32 v50, vcc, 0x824b000, v50
	global_load_dwordx4 v[34:37], v[34:35], off offset:2560
	s_nop 0
	v_addc_co_u32_e32 v51, vcc, 0, v51, vcc
	global_load_dwordx4 v[42:45], v[42:43], off
	v_add_co_u32_e32 v58, vcc, 0x1a242000, v62
	v_lshl_add_u64 v[38:39], v[80:81], 0, s[20:21]
	s_mov_b64 exec, s[98:99]
	global_load_dwordx4 v[46:49], v[46:47], off
	s_mov_b64 exec, -1
	v_addc_co_u32_e32 v59, vcc, 0, v63, vcc
	global_load_dwordx4 v[38:41], v[38:39], off
	v_add_co_u32_e32 v62, vcc, 0x17242000, v62
	global_load_dwordx4 v[50:53], v[50:51], off offset:3072
	s_nop 0
	v_addc_co_u32_e32 v63, vcc, 0, v63, vcc
	v_lshl_add_u64 v[102:103], v[76:77], 0, s[20:21]
	global_load_dwordx4 v[58:61], v[58:59], off
	v_add_co_u32_e32 v98, vcc, 0x81f2000, v102
	v_lshl_add_u64 v[54:55], v[78:79], 0, s[20:21]
	s_mov_b64 exec, s[98:99]
	global_load_dwordx4 v[62:65], v[62:63], off
	s_mov_b64 exec, -1
	v_addc_co_u32_e32 v99, vcc, 0, v103, vcc
	global_load_dwordx4 v[54:57], v[54:55], off
	v_add_co_u32_e32 v102, vcc, 0x822e000, v102
	global_load_dwordx4 v[98:101], v[98:99], off offset:512
	s_nop 0
	v_addc_co_u32_e32 v103, vcc, 0, v103, vcc
	global_load_dwordx4 v[102:105], v[102:103], off offset:1536

; #define LDS_BARRIER() do { asm volatile("s_waitcnt lgkmcnt(0)" ::: "memory"); __builtin_amdgcn_s_barrier(); asm volatile("" ::: "memory"); } while (0)
; #define GDN_STORE_O(nn) do { const LAS bf16_t* ob_ = OTb + ((nn) & 1) * 4608; _Pragma("unroll") for (int k_ = 0; k_ < 2; ++k_) { const int vi_ = pt_ + 256 * k_, row_ = vi_ >> 3, c8_ = (vi_ & 7) * 8; \
;             *(u32x4*)(Y + (size_t)(b * T_ + 64 * (nn) + row_) * D_ + 256 + h * 128 + 64 * dvh + c8_) = *(const LAS u32x4*)(ob_ + row_ * 72 + c8_); } } while (0)
; __device__ __forceinline__ void gdn_scan(const Ctx& c, const Params& p, int e) {
;     ...
;         if (producer) {
;             int pt_ = ptid; asm volatile("" : "+v"(pt_));
;             u32x4 tq[4], tk[4], tw[4], tu[4], tqk[2];
;             const int prow = pt_ >> 4, pc8 = (pt_ & 15) * 8;
;             const int qrow = pt_ >> 3, qc8 = (pt_ & 7) * 8;
;             GDN_LOAD_TILES(0); GDN_STORE_TILES();
;             for (int n = 0; n < 128; ++n) {
;                 LDS_BARRIER();
;                 if (n + 1 < 128) GDN_LOAD_TILES(n + 1);
;                 if (n >= 1) GDN_STORE_O(n - 1);
;                 LDS_BARRIER();
;                 if (n + 1 < 128) GDN_STORE_TILES();
.Lgp_e_wr:
	ds_write_b128 v91, v[116:119]
	ds_write_b128 v91, v[120:123] offset:17408
	ds_write_b128 v91, v[124:127] offset:34816
	ds_write_b128 v92, v[128:131] offset:52224
	ds_write_b128 v91, v[132:135] offset:4352
	ds_write_b128 v91, v[136:139] offset:21760
	ds_write_b128 v91, v[140:143] offset:39168
	ds_write_b128 v93, v[200:203] offset:52224
	ds_write_b128 v91, v[204:207] offset:8704
	ds_write_b128 v91, v[208:211] offset:26112
	ds_write_b128 v91, v[212:215] offset:43520
	ds_write_b128 v94, v[216:219] offset:52224
	ds_write_b128 v91, v[220:223] offset:13056
	ds_write_b128 v91, v[224:227] offset:30464
	ds_write_b128 v91, v[228:231] offset:47872
	ds_write_b128 v95, v[232:235] offset:52224
	ds_write_b128 v96, v[236:239]
	ds_write_b128 v96, v[240:243] offset:4608
	s_cmpk_eq_i32 s2, 0x7e
	s_cbranch_scc1 .Lgp_done
	s_waitcnt lgkmcnt(0)
	s_barrier
	s_bitcmp1_b32 s2, 0
	s_cselect_b32 s3, 0x2400, 0
	v_add_u32_e32 v73, s3, v69
	v_add_u32_e32 v75, v73, v90
	ds_read_b128 v[106:109], v75
	v_ashrrev_i32_e32 v75, 31, v74
	v_lshlrev_b64 v[110:111], 11, v[74:75]
	v_lshl_add_u64 v[110:111], v[70:71], 0, v[110:111]
	v_add_u32_e32 v73, v73, v67
	s_waitcnt lgkmcnt(0)
	global_store_dwordx4 v[110:111], v[106:109], off offset:512
	ds_read_b128 v[106:109], v73
	v_ashrrev_i32_e32 v73, 31, v72
	v_lshlrev_b64 v[110:111], 11, v[72:73]
	v_lshl_add_u64 v[110:111], v[70:71], 0, v[110:111]
	s_waitcnt lgkmcnt(0)
	global_store_dwordx4 v[110:111], v[106:109], off offset:512
	v_lshl_add_u64 v[220:221], v[84:85], 0, s[20:21]
	v_add_co_u32_e32 v116, vcc, 0x81f1000, v220
	v_lshl_add_u64 v[228:229], v[88:89], 0, s[20:21]
	s_nop 0
	v_addc_co_u32_e32 v117, vcc, 0, v221, vcc
	v_add_co_u32_e32 v120, vcc, 0x1a230000, v228
	s_nop 0
	v_addc_co_u32_e32 v121, vcc, 0, v229, vcc
	v_add_co_u32_e32 v124, vcc, 0x17230000, v228
	global_load_dwordx4 v[116:119], v[116:117], off offset:1536
	s_nop 0
	v_addc_co_u32_e32 v125, vcc, 0, v229, vcc
	v_add_co_u32_e32 v132, vcc, 0x820f000, v220
	global_load_dwordx4 v[120:123], v[120:121], off
	s_nop 0
	v_addc_co_u32_e32 v133, vcc, 0, v221, vcc
	v_add_co_u32_e32 v136, vcc, 0x1a236000, v228
	v_lshl_add_u64 v[128:129], v[86:87], 0, s[20:21]
	s_nop 0
	v_addc_co_u32_e32 v137, vcc, 0, v229, vcc
	v_add_co_u32_e32 v140, vcc, 0x17236000, v228
	s_mov_b64 exec, s[98:99]
	global_load_dwordx4 v[124:127], v[124:125], off
	s_mov_b64 exec, -1
	s_nop 0
	v_addc_co_u32_e32 v141, vcc, 0, v229, vcc
	v_add_co_u32_e32 v204, vcc, 0x822d000, v220
	global_load_dwordx4 v[128:131], v[128:129], off
	s_nop 0
	v_addc_co_u32_e32 v205, vcc, 0, v221, vcc
	v_add_co_u32_e32 v208, vcc, 0x1a23c000, v228
	global_load_dwordx4 v[132:135], v[132:133], off offset:2048
	s_nop 0
	v_addc_co_u32_e32 v209, vcc, 0, v229, vcc
	global_load_dwordx4 v[136:139], v[136:137], off
	v_add_co_u32_e32 v212, vcc, 0x1723c000, v228
	v_lshl_add_u64 v[200:201], v[82:83], 0, s[20:21]
	s_mov_b64 exec, s[98:99]
	global_load_dwordx4 v[140:143], v[140:141], off
	s_mov_b64 exec, -1
	v_addc_co_u32_e32 v213, vcc, 0, v229, vcc
	global_load_dwordx4 v[200:203], v[200:201], off
	v_add_co_u32_e32 v220, vcc, 0x824b000, v220
	global_load_dwordx4 v[204:207], v[204:205], off offset:2560
	s_nop 0
	v_addc_co_u32_e32 v221, vcc, 0, v221, vcc
	global_load_dwordx4 v[208:211], v[208:209], off
	v_add_co_u32_e32 v224, vcc, 0x1a242000, v228
	v_lshl_add_u64 v[216:217], v[80:81], 0, s[20:21]
	s_mov_b64 exec, s[98:99]
	global_load_dwordx4 v[212:215], v[212:213], off
	s_mov_b64 exec, -1
	v_addc_co_u32_e32 v225, vcc, 0, v229, vcc
	global_load_dwordx4 v[216:219], v[216:217], off
	v_add_co_u32_e32 v228, vcc, 0x17242000, v228
	global_load_dwordx4 v[220:223], v[220:221], off offset:3072
	s_nop 0
	v_addc_co_u32_e32 v229, vcc, 0, v229, vcc
	v_lshl_add_u64 v[240:241], v[76:77], 0, s[20:21]
	global_load_dwordx4 v[224:227], v[224:225], off
	v_add_co_u32_e32 v236, vcc, 0x81f2000, v240
	v_lshl_add_u64 v[232:233], v[78:79], 0, s[20:21]
	s_mov_b64 exec, s[98:99]
	global_load_dwordx4 v[228:231], v[228:229], off
	s_mov_b64 exec, -1
	v_addc_co_u32_e32 v237, vcc, 0, v241, vcc
	global_load_dwordx4 v[232:235], v[232:233], off
	v_add_co_u32_e32 v240, vcc, 0x822e000, v240
	global_load_dwordx4 v[236:239], v[236:237], off offset:512
	s_nop 0
	v_addc_co_u32_e32 v241, vcc, 0, v241, vcc
	global_load_dwordx4 v[240:243], v[240:241], off offset:1536
	s_add_i32 s2, s2, 1
	s_waitcnt lgkmcnt(0)
	s_barrier
	s_mov_b64 s[40:41], 0x18000
	v_add_u32_e32 v72, 64, v72
	v_add_u32_e32 v74, 64, v74
	v_lshl_add_u64 v[76:77], v[76:77], 0, s[76:77]
	v_lshl_add_u64 v[78:79], v[78:79], 0, s[76:77]
	v_lshl_add_u64 v[80:81], v[80:81], 0, s[76:77]
	v_lshl_add_u64 v[82:83], v[82:83], 0, s[76:77]
	v_lshl_add_u64 v[84:85], v[84:85], 0, s[76:77]
	v_lshl_add_u64 v[86:87], v[86:87], 0, s[76:77]
	v_lshl_add_u64 v[88:89], v[88:89], 0, s[40:41]
	s_waitcnt vmcnt(18)
	ds_write_b128 v91, v[2:5]
	ds_write_b128 v91, v[10:13] offset:17408
	ds_write_b128 v91, v[14:17] offset:34816
	ds_write_b128 v92, v[6:9] offset:52224
	ds_write_b128 v91, v[18:21] offset:4352
	ds_write_b128 v91, v[26:29] offset:21760
	ds_write_b128 v91, v[30:33] offset:39168
	ds_write_b128 v93, v[22:25] offset:52224
	ds_write_b128 v91, v[34:37] offset:8704
	ds_write_b128 v91, v[42:45] offset:26112
	ds_write_b128 v91, v[46:49] offset:43520
	ds_write_b128 v94, v[38:41] offset:52224
	ds_write_b128 v91, v[50:53] offset:13056
	ds_write_b128 v91, v[58:61] offset:30464
	ds_write_b128 v91, v[62:65] offset:47872
	ds_write_b128 v95, v[54:57] offset:52224
	ds_write_b128 v96, v[98:101]
	ds_write_b128 v96, v[102:105] offset:4608
	s_branch .Lgp_even
